# m32 + index unit prologue: the 128 key registers are not zeroed per unit (every later read of K[jj] is guarded by jj < ntl and step A writes all of those)
# speedup vs baseline: 1.0047x; 1.0002x over previous
.Lidx_pw0:
	v_cndmask_b32_e64 v19, 0, 1, s[78:79]
	v_cmp_ne_u32_e64 s[28:29], 1, v19
	s_andn2_b64 vcc, exec, s[78:79]
	v_lshlrev_b32_e32 v39, 4, v36
	v_lshlrev_b32_e32 v172, 2, v167
	v_lshl_add_u32 v40, v167, 13, 0
	v_lshl_add_u32 v41, v18, 2, s14
	s_waitcnt lgkmcnt(0)
	s_barrier
	s_cbranch_vccnz .LBB0_1383
	s_add_i32 s0, s77, 8
	s_lshr_b32 s1, s0, 29
	s_add_i32 s0, s0, s1
	s_ashr_i32 s13, s0, 3
	s_add_i32 s0, 0, 0x22200
	v_add_u32_e32 v173, s0, v39
	v_readlane_b32 s0, v251, 29
	s_add_i32 s14, s13, -2
	s_add_i32 s15, s13, -3
	v_add_u32_e32 v174, s0, v39
	s_max_i32 s0, s13, 2
	s_lshl_b32 s0, s0, 3
	s_add_i32 s0, s0, -8
	s_and_b32 s16, s0, -16
	v_or_b32_e32 v175, s24, v167
	s_add_i32 s16, s16, 16
	s_mov_b32 s17, 0
	v_mov_b32_e32 v176, v41
	s_mov_b32 s18, 0
	s_mov_b32 s19, 0
	ds_read_b128 v[200:203], v173
	ds_read_b128 v[204:207], v173 offset:1024
	ds_read_b128 v[208:211], v173 offset:2048
	ds_read_b128 v[212:215], v173 offset:3072
	ds_read_b128 v[216:219], v173 offset:4096
	ds_read_b128 v[226:229], v173 offset:5120
	v_lshlrev_b32_e32 v246, 21, v172
	s_branch .LBB0_1296
